# v55 + dilated-window units rotated over idx per CU round (every CU gets the same mix of cheap q0=0 units)
# baseline (speedup 1.0000x reference)
.LBB0_670:
	s_add_i32 s23, s23, s72
	s_cmpk_lt_i32 s23, 0xc00
	s_cselect_b64 s[2:3], -1, 0
	s_cmpk_gt_i32 s23, 0xbff
	s_cselect_b64 s[16:17], -1, 0
	s_and_b64 vcc, exec, s[16:17]
	s_cbranch_vccnz .LBB0_677
	s_ashr_i32 s0, s23, 10
	s_lshr_b32 s8, s23, 8
	s_add_i32 s8, s8, s23
	s_and_b32 s8, s8, 31
	s_cmp_eq_u32 s0, 1
	s_cselect_b32 s1, 4, 16
	s_cselect_b32 s6, 2, 4
	s_cmpk_lt_u32 s23, 0x400
	s_cselect_b32 s9, 0, s6
	s_cselect_b32 s20, 1, s1
	s_sub_i32 s1, 5, s9
	s_lshl_b32 s6, s23, 5
	s_lshr_b32 s1, s8, s1
	s_and_b32 s6, s6, 0x6000
	s_or_b32 s18, s1, s6
	s_cmp_gt_i32 s0, 1
	s_mov_b64 s[6:7], -1
	s_cbranch_scc0 .LBB0_673
	s_lshl_b32 s1, s18, 11
	s_add_u32 s1, s30, s1
	s_addc_u32 s6, s31, 0
	s_add_u32 s14, s1, 0x400
	s_addc_u32 s15, s6, 0
	s_mov_b64 s[6:7], 0

.LBB0_1961:
	s_add_i32 s23, s23, s72
	s_cmpk_lt_i32 s23, 0xc00
	s_cselect_b64 s[2:3], -1, 0
	s_cmpk_gt_i32 s23, 0xbff
	s_cselect_b64 s[16:17], -1, 0
	s_and_b64 vcc, exec, s[16:17]
	s_cbranch_vccnz .LBB0_1968
	s_ashr_i32 s0, s23, 10
	s_lshr_b32 s8, s23, 8
	s_add_i32 s8, s8, s23
	s_and_b32 s8, s8, 31
	s_cmp_eq_u32 s0, 1
	s_cselect_b32 s1, 4, 16
	s_cselect_b32 s6, 2, 4
	s_cmpk_lt_u32 s23, 0x400
	s_cselect_b32 s9, 0, s6
	s_cselect_b32 s51, 1, s1
	s_sub_i32 s1, 5, s9
	s_lshl_b32 s6, s23, 5
	s_lshr_b32 s1, s8, s1
	s_and_b32 s6, s6, 0x6000
	s_or_b32 s18, s1, s6
	s_cmp_gt_i32 s0, 1
	s_mov_b64 s[6:7], -1
	s_cbranch_scc0 .LBB0_1964
	s_lshl_b32 s1, s18, 11
	s_add_u32 s1, s30, s1
	s_addc_u32 s6, s31, 0
	s_add_u32 s14, s1, 0x400
	s_addc_u32 s15, s6, 0
	s_mov_b64 s[6:7], 0
